# attention combine block rewritten: one sqrt/div chain per lane (row=lane&15) + ds_bpermute redistribution instead of 16 redundant chains; in-place combine, reads 6 deep, subln weights loaded at block
# speedup vs baseline: 1.0066x; 1.0066x over previous
; __device__ __forceinline__ float shx(float v, int o, int lane) { return __int_as_float(__builtin_amdgcn_ds_bpermute((lane ^ o) << 2, __float_as_int(v))); }
; __device__ __forceinline__ int crow(int r, int hi) { return (r & 3) + 8 * (r >> 2) + 4 * hi; }
; __device__ __forceinline__ void attn_unit(LAS unsigned char* lds, bf16_t* Zg, const unsigned char* KVg, int S, int b, int h, int qb, const float* lq1, const float* lk1, const float* lq2, const float* lk2, const float* subln_g, const float* rel_bias, bool dostore = true) {
;     ...
;     __syncthreads();
;     if (mp == 0) {
;         float ss[16];
; #pragma unroll
;         for (int r = 0; r < 16; ++r) { float a = 0.f;
; #pragma unroll
;             for (int db = 0; db < 4; ++db) { const float d = o[db][r] * inv[r] - exch[(32 * qsub + crow(r, hi)) * 128 + db * 32 + r32]; o[db][r] = d; a += d * d; }
;             ss[r] = a; }
; #pragma unroll
;         for (int r = 0; r < 16; ++r) {
; #pragma unroll
;             for (int sft = 1; sft < 32; sft <<= 1) ss[r] += shx(ss[r], sft, lane);
;             ss[r] = (1.0f - LAMBDA_INIT) / sqrtf(ss[r] * (1.0f / 128.0f) + EPS); }
; #pragma unroll
;         for (int db = 0; db < 4; ++db) { const float sg = subln_g[db * 32 + r32];
.LBB0_287:
	s_cmpk_gt_u32 s15, 0xff
	s_waitcnt lgkmcnt(0)
	s_barrier
	s_cbranch_scc1 .LBB0_187
	v_or_b32_e32 v0, s84, v211
	v_lshlrev_b32_e32 v0, 9, v0
	v_add3_u32 v0, 0, v82, v0
	global_load_dword v190, v82, s[68:69]
	global_load_dword v191, v82, s[68:69] offset:128
	global_load_dword v192, v82, s[68:69] offset:256
	global_load_dword v193, v82, s[68:69] offset:384
	v_add_u32_e32 v105, 0x400, v0
	v_add_u32_e32 v106, 0x1000, v0
	v_add_u32_e32 v107, 0x1400, v0
	v_add_u32_e32 v108, 0x2000, v0
	v_add_u32_e32 v109, 0x2400, v0
	v_add_u32_e32 v110, 0x3000, v0
	v_add_u32_e32 v111, 0x3400, v0
	ds_read2_b32 v[178:179], v0 offset1:32
	ds_read2_b32 v[180:181], v0 offset0:64 offset1:96
	ds_read2_b32 v[182:183], v0 offset0:128 offset1:160
	ds_read2_b32 v[184:185], v0 offset0:192 offset1:224
	ds_read2_b32 v[186:187], v105 offset1:32
	ds_read2_b32 v[188:189], v105 offset0:64 offset1:96
	s_waitcnt lgkmcnt(5)
	v_fma_f32 v50, v50, v78, -v178
	v_fma_f32 v34, v34, v78, -v179
	ds_read2_b32 v[178:179], v105 offset0:128 offset1:160
	s_waitcnt lgkmcnt(5)
	v_fma_f32 v18, v18, v78, -v180
	v_fma_f32 v2, v2, v78, -v181
	ds_read2_b32 v[180:181], v105 offset0:192 offset1:224
	v_mul_f32_e32 v89, v34, v34
	v_fmac_f32_e32 v89, v50, v50
	v_fmac_f32_e32 v89, v18, v18
	v_fmac_f32_e32 v89, v2, v2
	s_waitcnt lgkmcnt(5)
	v_fma_f32 v51, v51, v79, -v182
	v_fma_f32 v35, v35, v79, -v183
	ds_read2_b32 v[182:183], v106 offset1:32
	s_waitcnt lgkmcnt(5)
	v_fma_f32 v19, v19, v79, -v184
	v_fma_f32 v3, v3, v79, -v185
	ds_read2_b32 v[184:185], v106 offset0:64 offset1:96
	v_mul_f32_e32 v90, v35, v35
	v_fmac_f32_e32 v90, v51, v51
	v_fmac_f32_e32 v90, v19, v19
	v_fmac_f32_e32 v90, v3, v3
	s_waitcnt lgkmcnt(5)
	v_fma_f32 v52, v52, v80, -v186
	v_fma_f32 v36, v36, v80, -v187
	ds_read2_b32 v[186:187], v106 offset0:128 offset1:160
	s_waitcnt lgkmcnt(5)
	v_fma_f32 v20, v20, v80, -v188
	v_fma_f32 v4, v4, v80, -v189
	ds_read2_b32 v[188:189], v106 offset0:192 offset1:224
	v_mul_f32_e32 v91, v36, v36
	v_fmac_f32_e32 v91, v52, v52
	v_fmac_f32_e32 v91, v20, v20
	v_fmac_f32_e32 v91, v4, v4
	s_waitcnt lgkmcnt(5)
	v_fma_f32 v53, v53, v81, -v178
	v_fma_f32 v37, v37, v81, -v179
	ds_read2_b32 v[178:179], v107 offset1:32
	s_waitcnt lgkmcnt(5)
	v_fma_f32 v21, v21, v81, -v180
	v_fma_f32 v5, v5, v81, -v181
	ds_read2_b32 v[180:181], v107 offset0:64 offset1:96
	v_mul_f32_e32 v92, v37, v37
	v_fmac_f32_e32 v92, v53, v53
	v_fmac_f32_e32 v92, v21, v21
	v_fmac_f32_e32 v92, v5, v5
	s_waitcnt lgkmcnt(5)
	v_fma_f32 v54, v54, v74, -v182
	v_fma_f32 v38, v38, v74, -v183
	ds_read2_b32 v[182:183], v107 offset0:128 offset1:160
	s_waitcnt lgkmcnt(5)
	v_fma_f32 v22, v22, v74, -v184
	v_fma_f32 v6, v6, v74, -v185
	ds_read2_b32 v[184:185], v107 offset0:192 offset1:224
	v_mul_f32_e32 v93, v38, v38
	v_fmac_f32_e32 v93, v54, v54
	v_fmac_f32_e32 v93, v22, v22
	v_fmac_f32_e32 v93, v6, v6
	s_waitcnt lgkmcnt(5)
	v_fma_f32 v55, v55, v75, -v186
	v_fma_f32 v39, v39, v75, -v187
	ds_read2_b32 v[186:187], v108 offset1:32
	s_waitcnt lgkmcnt(5)
	v_fma_f32 v23, v23, v75, -v188
	v_fma_f32 v7, v7, v75, -v189
	ds_read2_b32 v[188:189], v108 offset0:64 offset1:96
	v_mul_f32_e32 v94, v39, v39
	v_fmac_f32_e32 v94, v55, v55
	v_fmac_f32_e32 v94, v23, v23
	v_fmac_f32_e32 v94, v7, v7
	s_waitcnt lgkmcnt(5)
	v_fma_f32 v56, v56, v76, -v178
	v_fma_f32 v40, v40, v76, -v179
	ds_read2_b32 v[178:179], v108 offset0:128 offset1:160
	s_waitcnt lgkmcnt(5)
	v_fma_f32 v24, v24, v76, -v180
	v_fma_f32 v8, v8, v76, -v181
	ds_read2_b32 v[180:181], v108 offset0:192 offset1:224
	v_mul_f32_e32 v95, v40, v40
	v_fmac_f32_e32 v95, v56, v56
	v_fmac_f32_e32 v95, v24, v24
	v_fmac_f32_e32 v95, v8, v8
	s_waitcnt lgkmcnt(5)
	v_fma_f32 v57, v57, v77, -v182
	v_fma_f32 v41, v41, v77, -v183
	ds_read2_b32 v[182:183], v109 offset1:32
	s_waitcnt lgkmcnt(5)
	v_fma_f32 v25, v25, v77, -v184
	v_fma_f32 v9, v9, v77, -v185
	ds_read2_b32 v[184:185], v109 offset0:64 offset1:96
	v_mul_f32_e32 v96, v41, v41
	v_fmac_f32_e32 v96, v57, v57
	v_fmac_f32_e32 v96, v25, v25
	v_fmac_f32_e32 v96, v9, v9
	s_waitcnt lgkmcnt(5)
	v_fma_f32 v58, v58, v70, -v186
	v_fma_f32 v42, v42, v70, -v187
	ds_read2_b32 v[186:187], v109 offset0:128 offset1:160
	s_waitcnt lgkmcnt(5)
	v_fma_f32 v26, v26, v70, -v188
	v_fma_f32 v10, v10, v70, -v189
	ds_read2_b32 v[188:189], v109 offset0:192 offset1:224
	v_mul_f32_e32 v97, v42, v42
	v_fmac_f32_e32 v97, v58, v58
	v_fmac_f32_e32 v97, v26, v26
	v_fmac_f32_e32 v97, v10, v10
	s_waitcnt lgkmcnt(5)
	v_fma_f32 v59, v59, v71, -v178
	v_fma_f32 v43, v43, v71, -v179
	ds_read2_b32 v[178:179], v110 offset1:32
	s_waitcnt lgkmcnt(5)
	v_fma_f32 v27, v27, v71, -v180
	v_fma_f32 v11, v11, v71, -v181
	ds_read2_b32 v[180:181], v110 offset0:64 offset1:96
	v_mul_f32_e32 v98, v43, v43
	v_fmac_f32_e32 v98, v59, v59
	v_fmac_f32_e32 v98, v27, v27
	v_fmac_f32_e32 v98, v11, v11
	s_waitcnt lgkmcnt(5)
	v_fma_f32 v60, v60, v72, -v182
	v_fma_f32 v44, v44, v72, -v183
	ds_read2_b32 v[182:183], v110 offset0:128 offset1:160
	s_waitcnt lgkmcnt(5)
	v_fma_f32 v28, v28, v72, -v184
	v_fma_f32 v12, v12, v72, -v185
	ds_read2_b32 v[184:185], v110 offset0:192 offset1:224
	v_mul_f32_e32 v99, v44, v44
	v_fmac_f32_e32 v99, v60, v60
	v_fmac_f32_e32 v99, v28, v28
	v_fmac_f32_e32 v99, v12, v12
	s_waitcnt lgkmcnt(5)
	v_fma_f32 v61, v61, v73, -v186
	v_fma_f32 v45, v45, v73, -v187
	ds_read2_b32 v[186:187], v111 offset1:32
	s_waitcnt lgkmcnt(5)
	v_fma_f32 v29, v29, v73, -v188
	v_fma_f32 v13, v13, v73, -v189
	ds_read2_b32 v[188:189], v111 offset0:64 offset1:96
	v_mul_f32_e32 v100, v45, v45
	v_fmac_f32_e32 v100, v61, v61
	v_fmac_f32_e32 v100, v29, v29
	v_fmac_f32_e32 v100, v13, v13
	s_waitcnt lgkmcnt(5)
; __device__ __forceinline__ float shx(float v, int o, int lane) { return __int_as_float(__builtin_amdgcn_ds_bpermute((lane ^ o) << 2, __float_as_int(v))); }
; __device__ __forceinline__ int crow(int r, int hi) { return (r & 3) + 8 * (r >> 2) + 4 * hi; }
; __device__ __forceinline__ void attn_unit(LAS unsigned char* lds, bf16_t* Zg, const unsigned char* KVg, int S, int b, int h, int qb, const float* lq1, const float* lk1, const float* lq2, const float* lk2, const float* subln_g, const float* rel_bias, bool dostore = true) {
;     ...
;         for (int r = 0; r < 16; ++r) { float a = 0.f;
; #pragma unroll
;             for (int db = 0; db < 4; ++db) { const float d = o[db][r] * inv[r] - exch[(32 * qsub + crow(r, hi)) * 128 + db * 32 + r32]; o[db][r] = d; a += d * d; }
;             ss[r] = a; }
; #pragma unroll
;         for (int r = 0; r < 16; ++r) {
; #pragma unroll
;             for (int sft = 1; sft < 32; sft <<= 1) ss[r] += shx(ss[r], sft, lane);
	v_fma_f32 v62, v62, v66, -v178
	v_fma_f32 v46, v46, v66, -v179
	ds_read2_b32 v[178:179], v111 offset0:128 offset1:160
	s_waitcnt lgkmcnt(5)
	v_fma_f32 v30, v30, v66, -v180
	v_fma_f32 v14, v14, v66, -v181
	ds_read2_b32 v[180:181], v111 offset0:192 offset1:224
	v_mul_f32_e32 v101, v46, v46
	v_fmac_f32_e32 v101, v62, v62
	v_fmac_f32_e32 v101, v30, v30
	v_fmac_f32_e32 v101, v14, v14
	s_waitcnt lgkmcnt(5)
	v_fma_f32 v63, v63, v67, -v182
	v_fma_f32 v47, v47, v67, -v183
	s_waitcnt lgkmcnt(4)
	v_fma_f32 v31, v31, v67, -v184
	v_fma_f32 v15, v15, v67, -v185
	v_mul_f32_e32 v102, v47, v47
	v_fmac_f32_e32 v102, v63, v63
	v_fmac_f32_e32 v102, v31, v31
	v_fmac_f32_e32 v102, v15, v15
	s_waitcnt lgkmcnt(3)
	v_fma_f32 v64, v64, v68, -v186
	v_fma_f32 v48, v48, v68, -v187
	s_waitcnt lgkmcnt(2)
	v_fma_f32 v32, v32, v68, -v188
	v_fma_f32 v16, v16, v68, -v189
	v_mul_f32_e32 v103, v48, v48
	v_fmac_f32_e32 v103, v64, v64
	v_fmac_f32_e32 v103, v32, v32
	v_fmac_f32_e32 v103, v16, v16
	s_waitcnt lgkmcnt(1)
	v_fma_f32 v65, v65, v69, -v178
	v_fma_f32 v49, v49, v69, -v179
	s_waitcnt lgkmcnt(0)
	v_fma_f32 v33, v33, v69, -v180
	v_fma_f32 v17, v17, v69, -v181
	v_mul_f32_e32 v104, v49, v49
	v_fmac_f32_e32 v104, v65, v65
	v_fmac_f32_e32 v104, v33, v33
	v_fmac_f32_e32 v104, v17, v17
	s_nop 1
	v_mov_b32_dpp v84, v89 quad_perm:[1,0,3,2] row_mask:0xf bank_mask:0xf
	v_mov_b32_dpp v85, v90 quad_perm:[1,0,3,2] row_mask:0xf bank_mask:0xf
	v_mov_b32_dpp v86, v91 quad_perm:[1,0,3,2] row_mask:0xf bank_mask:0xf
	v_mov_b32_dpp v87, v92 quad_perm:[1,0,3,2] row_mask:0xf bank_mask:0xf
	v_add_f32_e32 v89, v89, v84
	v_add_f32_e32 v90, v90, v85
	v_add_f32_e32 v91, v91, v86
	v_add_f32_e32 v92, v92, v87
	v_mov_b32_dpp v84, v89 quad_perm:[2,3,0,1] row_mask:0xf bank_mask:0xf
	v_mov_b32_dpp v85, v90 quad_perm:[2,3,0,1] row_mask:0xf bank_mask:0xf
	v_mov_b32_dpp v86, v91 quad_perm:[2,3,0,1] row_mask:0xf bank_mask:0xf
	v_mov_b32_dpp v87, v92 quad_perm:[2,3,0,1] row_mask:0xf bank_mask:0xf
	v_add_f32_e32 v89, v89, v84
	v_add_f32_e32 v90, v90, v85
	v_add_f32_e32 v91, v91, v86
	v_add_f32_e32 v92, v92, v87
	v_mov_b32_dpp v84, v89 row_half_mirror row_mask:0xf bank_mask:0xf
	v_mov_b32_dpp v85, v90 row_half_mirror row_mask:0xf bank_mask:0xf
	v_mov_b32_dpp v86, v91 row_half_mirror row_mask:0xf bank_mask:0xf
	v_mov_b32_dpp v87, v92 row_half_mirror row_mask:0xf bank_mask:0xf
	v_add_f32_e32 v89, v89, v84
	v_add_f32_e32 v90, v90, v85
	v_add_f32_e32 v91, v91, v86
	v_add_f32_e32 v92, v92, v87
	v_mov_b32_dpp v84, v89 row_ror:8 row_mask:0xf bank_mask:0xf
	v_mov_b32_dpp v85, v90 row_ror:8 row_mask:0xf bank_mask:0xf
	v_mov_b32_dpp v86, v91 row_ror:8 row_mask:0xf bank_mask:0xf
	v_mov_b32_dpp v87, v92 row_ror:8 row_mask:0xf bank_mask:0xf
	v_add_f32_e32 v89, v89, v84
	v_add_f32_e32 v90, v90, v85
	v_add_f32_e32 v91, v91, v86
	v_add_f32_e32 v92, v92, v87
	v_mov_b32_e32 v84, v89
	v_mov_b32_e32 v85, v90
	v_mov_b32_e32 v86, v91
	v_mov_b32_e32 v87, v92
	v_permlane16_swap_b32_e32 v84, v89
	v_permlane16_swap_b32_e32 v85, v90
	v_permlane16_swap_b32_e32 v86, v91
	v_permlane16_swap_b32_e32 v87, v92
	v_add_f32_e32 v89, v89, v84
	v_add_f32_e32 v90, v90, v85
	v_add_f32_e32 v91, v91, v86
	v_add_f32_e32 v92, v92, v87
	s_nop 1
	v_mov_b32_dpp v84, v93 quad_perm:[1,0,3,2] row_mask:0xf bank_mask:0xf
	v_mov_b32_dpp v85, v94 quad_perm:[1,0,3,2] row_mask:0xf bank_mask:0xf
	v_mov_b32_dpp v86, v95 quad_perm:[1,0,3,2] row_mask:0xf bank_mask:0xf
	v_mov_b32_dpp v87, v96 quad_perm:[1,0,3,2] row_mask:0xf bank_mask:0xf
	v_add_f32_e32 v93, v93, v84
	v_add_f32_e32 v94, v94, v85
	v_add_f32_e32 v95, v95, v86
	v_add_f32_e32 v96, v96, v87
	v_mov_b32_dpp v84, v93 quad_perm:[2,3,0,1] row_mask:0xf bank_mask:0xf
	v_mov_b32_dpp v85, v94 quad_perm:[2,3,0,1] row_mask:0xf bank_mask:0xf
	v_mov_b32_dpp v86, v95 quad_perm:[2,3,0,1] row_mask:0xf bank_mask:0xf
	v_mov_b32_dpp v87, v96 quad_perm:[2,3,0,1] row_mask:0xf bank_mask:0xf
	v_add_f32_e32 v93, v93, v84
	v_add_f32_e32 v94, v94, v85
	v_add_f32_e32 v95, v95, v86
	v_add_f32_e32 v96, v96, v87
	v_mov_b32_dpp v84, v93 row_half_mirror row_mask:0xf bank_mask:0xf
	v_mov_b32_dpp v85, v94 row_half_mirror row_mask:0xf bank_mask:0xf
	v_mov_b32_dpp v86, v95 row_half_mirror row_mask:0xf bank_mask:0xf
	v_mov_b32_dpp v87, v96 row_half_mirror row_mask:0xf bank_mask:0xf
	v_add_f32_e32 v93, v93, v84
	v_add_f32_e32 v94, v94, v85
	v_add_f32_e32 v95, v95, v86
	v_add_f32_e32 v96, v96, v87
	v_mov_b32_dpp v84, v93 row_ror:8 row_mask:0xf bank_mask:0xf
	v_mov_b32_dpp v85, v94 row_ror:8 row_mask:0xf bank_mask:0xf
	v_mov_b32_dpp v86, v95 row_ror:8 row_mask:0xf bank_mask:0xf
	v_mov_b32_dpp v87, v96 row_ror:8 row_mask:0xf bank_mask:0xf
	v_add_f32_e32 v93, v93, v84
	v_add_f32_e32 v94, v94, v85
	v_add_f32_e32 v95, v95, v86
	v_add_f32_e32 v96, v96, v87
	v_mov_b32_e32 v84, v93
	v_mov_b32_e32 v85, v94
	v_mov_b32_e32 v86, v95
	v_mov_b32_e32 v87, v96
	v_permlane16_swap_b32_e32 v84, v93
	v_permlane16_swap_b32_e32 v85, v94
	v_permlane16_swap_b32_e32 v86, v95
	v_permlane16_swap_b32_e32 v87, v96
	v_add_f32_e32 v93, v93, v84
	v_add_f32_e32 v94, v94, v85
	v_add_f32_e32 v95, v95, v86
	v_add_f32_e32 v96, v96, v87
	s_nop 1
	v_mov_b32_dpp v84, v97 quad_perm:[1,0,3,2] row_mask:0xf bank_mask:0xf
	v_mov_b32_dpp v85, v98 quad_perm:[1,0,3,2] row_mask:0xf bank_mask:0xf
	v_mov_b32_dpp v86, v99 quad_perm:[1,0,3,2] row_mask:0xf bank_mask:0xf
	v_mov_b32_dpp v87, v100 quad_perm:[1,0,3,2] row_mask:0xf bank_mask:0xf
	v_add_f32_e32 v97, v97, v84
	v_add_f32_e32 v98, v98, v85
	v_add_f32_e32 v99, v99, v86
	v_add_f32_e32 v100, v100, v87
	v_mov_b32_dpp v84, v97 quad_perm:[2,3,0,1] row_mask:0xf bank_mask:0xf
	v_mov_b32_dpp v85, v98 quad_perm:[2,3,0,1] row_mask:0xf bank_mask:0xf
; __device__ __forceinline__ float shx(float v, int o, int lane) { return __int_as_float(__builtin_amdgcn_ds_bpermute((lane ^ o) << 2, __float_as_int(v))); }
; __device__ __forceinline__ void attn_unit(LAS unsigned char* lds, bf16_t* Zg, const unsigned char* KVg, int S, int b, int h, int qb, const float* lq1, const float* lk1, const float* lq2, const float* lk2, const float* subln_g, const float* rel_bias, bool dostore = true) {
;     ...
;         for (int r = 0; r < 16; ++r) {
; #pragma unroll
;             for (int sft = 1; sft < 32; sft <<= 1) ss[r] += shx(ss[r], sft, lane);
;             ss[r] = (1.0f - LAMBDA_INIT) / sqrtf(ss[r] * (1.0f / 128.0f) + EPS); }
	v_mov_b32_dpp v86, v99 quad_perm:[2,3,0,1] row_mask:0xf bank_mask:0xf
	v_mov_b32_dpp v87, v100 quad_perm:[2,3,0,1] row_mask:0xf bank_mask:0xf
	v_add_f32_e32 v97, v97, v84
	v_add_f32_e32 v98, v98, v85
	v_add_f32_e32 v99, v99, v86
	v_add_f32_e32 v100, v100, v87
	v_mov_b32_dpp v84, v97 row_half_mirror row_mask:0xf bank_mask:0xf
	v_mov_b32_dpp v85, v98 row_half_mirror row_mask:0xf bank_mask:0xf
	v_mov_b32_dpp v86, v99 row_half_mirror row_mask:0xf bank_mask:0xf
	v_mov_b32_dpp v87, v100 row_half_mirror row_mask:0xf bank_mask:0xf
	v_add_f32_e32 v97, v97, v84
	v_add_f32_e32 v98, v98, v85
	v_add_f32_e32 v99, v99, v86
	v_add_f32_e32 v100, v100, v87
	v_mov_b32_dpp v84, v97 row_ror:8 row_mask:0xf bank_mask:0xf
	v_mov_b32_dpp v85, v98 row_ror:8 row_mask:0xf bank_mask:0xf
	v_mov_b32_dpp v86, v99 row_ror:8 row_mask:0xf bank_mask:0xf
	v_mov_b32_dpp v87, v100 row_ror:8 row_mask:0xf bank_mask:0xf
	v_add_f32_e32 v97, v97, v84
	v_add_f32_e32 v98, v98, v85
	v_add_f32_e32 v99, v99, v86
	v_add_f32_e32 v100, v100, v87
	v_mov_b32_e32 v84, v97
	v_mov_b32_e32 v85, v98
	v_mov_b32_e32 v86, v99
	v_mov_b32_e32 v87, v100
	v_permlane16_swap_b32_e32 v84, v97
	v_permlane16_swap_b32_e32 v85, v98
	v_permlane16_swap_b32_e32 v86, v99
	v_permlane16_swap_b32_e32 v87, v100
	v_add_f32_e32 v97, v97, v84
	v_add_f32_e32 v98, v98, v85
	v_add_f32_e32 v99, v99, v86
	v_add_f32_e32 v100, v100, v87
	s_nop 1
	v_mov_b32_dpp v84, v101 quad_perm:[1,0,3,2] row_mask:0xf bank_mask:0xf
	v_mov_b32_dpp v85, v102 quad_perm:[1,0,3,2] row_mask:0xf bank_mask:0xf
	v_mov_b32_dpp v86, v103 quad_perm:[1,0,3,2] row_mask:0xf bank_mask:0xf
	v_mov_b32_dpp v87, v104 quad_perm:[1,0,3,2] row_mask:0xf bank_mask:0xf
	v_add_f32_e32 v101, v101, v84
	v_add_f32_e32 v102, v102, v85
	v_add_f32_e32 v103, v103, v86
	v_add_f32_e32 v104, v104, v87
	v_mov_b32_dpp v84, v101 quad_perm:[2,3,0,1] row_mask:0xf bank_mask:0xf
	v_mov_b32_dpp v85, v102 quad_perm:[2,3,0,1] row_mask:0xf bank_mask:0xf
	v_mov_b32_dpp v86, v103 quad_perm:[2,3,0,1] row_mask:0xf bank_mask:0xf
	v_mov_b32_dpp v87, v104 quad_perm:[2,3,0,1] row_mask:0xf bank_mask:0xf
	v_add_f32_e32 v101, v101, v84
	v_add_f32_e32 v102, v102, v85
	v_add_f32_e32 v103, v103, v86
	v_add_f32_e32 v104, v104, v87
	v_mov_b32_dpp v84, v101 row_half_mirror row_mask:0xf bank_mask:0xf
	v_mov_b32_dpp v85, v102 row_half_mirror row_mask:0xf bank_mask:0xf
	v_mov_b32_dpp v86, v103 row_half_mirror row_mask:0xf bank_mask:0xf
	v_mov_b32_dpp v87, v104 row_half_mirror row_mask:0xf bank_mask:0xf
	v_add_f32_e32 v101, v101, v84
	v_add_f32_e32 v102, v102, v85
	v_add_f32_e32 v103, v103, v86
	v_add_f32_e32 v104, v104, v87
	v_mov_b32_dpp v84, v101 row_ror:8 row_mask:0xf bank_mask:0xf
	v_mov_b32_dpp v85, v102 row_ror:8 row_mask:0xf bank_mask:0xf
	v_mov_b32_dpp v86, v103 row_ror:8 row_mask:0xf bank_mask:0xf
	v_mov_b32_dpp v87, v104 row_ror:8 row_mask:0xf bank_mask:0xf
	v_add_f32_e32 v101, v101, v84
	v_add_f32_e32 v102, v102, v85
	v_add_f32_e32 v103, v103, v86
	v_add_f32_e32 v104, v104, v87
	v_mov_b32_e32 v84, v101
	v_mov_b32_e32 v85, v102
	v_mov_b32_e32 v86, v103
	v_mov_b32_e32 v87, v104
	v_permlane16_swap_b32_e32 v84, v101
	v_permlane16_swap_b32_e32 v85, v102
	v_permlane16_swap_b32_e32 v86, v103
	v_permlane16_swap_b32_e32 v87, v104
	v_add_f32_e32 v101, v101, v84
	v_add_f32_e32 v102, v102, v85
	v_add_f32_e32 v103, v103, v86
	v_add_f32_e32 v104, v104, v87
	v_bfe_u32 v86, v82, 2, 4
	v_mov_b32_e32 v88, v89
	v_cmp_eq_u32_e32 vcc, 1, v86
	v_cmp_eq_u32_e64 s[4:5], 2, v86
	s_nop 0
	v_cndmask_b32_e32 v88, v88, v90, vcc
	v_cndmask_b32_e64 v88, v88, v91, s[4:5]
	v_cmp_eq_u32_e32 vcc, 3, v86
	v_cmp_eq_u32_e64 s[4:5], 4, v86
	s_nop 0
	v_cndmask_b32_e32 v88, v88, v92, vcc
	v_cndmask_b32_e64 v88, v88, v93, s[4:5]
	v_cmp_eq_u32_e32 vcc, 5, v86
	v_cmp_eq_u32_e64 s[4:5], 6, v86
	s_nop 0
	v_cndmask_b32_e32 v88, v88, v94, vcc
	v_cndmask_b32_e64 v88, v88, v95, s[4:5]
	v_cmp_eq_u32_e32 vcc, 7, v86
	v_cmp_eq_u32_e64 s[4:5], 8, v86
	s_nop 0
	v_cndmask_b32_e32 v88, v88, v96, vcc
	v_cndmask_b32_e64 v88, v88, v97, s[4:5]
	v_cmp_eq_u32_e32 vcc, 9, v86
	v_cmp_eq_u32_e64 s[4:5], 10, v86
	s_nop 0
	v_cndmask_b32_e32 v88, v88, v98, vcc
	v_cndmask_b32_e64 v88, v88, v99, s[4:5]
	v_cmp_eq_u32_e32 vcc, 11, v86
	v_cmp_eq_u32_e64 s[4:5], 12, v86
	s_nop 0
	v_cndmask_b32_e32 v88, v88, v100, vcc
	v_cndmask_b32_e64 v88, v88, v101, s[4:5]
	v_cmp_eq_u32_e32 vcc, 13, v86
	v_cmp_eq_u32_e64 s[4:5], 14, v86
	s_nop 0
	v_cndmask_b32_e32 v88, v88, v102, vcc
	v_cndmask_b32_e64 v88, v88, v103, s[4:5]
	v_cmp_eq_u32_e32 vcc, 15, v86
	s_nop 0
	v_cndmask_b32_e32 v88, v88, v104, vcc
	v_fmamk_f32 v88, v88, 0x3c000000, v206
	v_cmp_gt_f32_e32 vcc, s36, v88
	v_mul_f32_e32 v178, 0x4f800000, v88
	s_nop 0
	v_cndmask_b32_e32 v88, v88, v178, vcc
	v_sqrt_f32_e32 v178, v88
	s_nop 0
	v_add_u32_e32 v179, -1, v178
	v_fma_f32 v180, -v179, v178, v88
	v_cmp_ge_f32_e64 s[4:5], 0, v180
	v_add_u32_e32 v180, 1, v178
	s_nop 0
	v_cndmask_b32_e64 v179, v178, v179, s[4:5]
	v_fma_f32 v178, -v180, v178, v88
	v_cmp_lt_f32_e64 s[4:5], 0, v178
	s_nop 1
	v_cndmask_b32_e64 v178, v179, v180, s[4:5]
	v_mul_f32_e32 v179, 0x37800000, v178
	v_cndmask_b32_e32 v178, v178, v179, vcc
	v_cmp_class_f32_e32 vcc, v88, v205
	s_nop 1
	v_cndmask_b32_e32 v88, v178, v88, vcc
	v_div_scale_f32 v178, s[4:5], v88, v88, s95
	v_rcp_f32_e32 v179, v178
	s_nop 0
	v_fma_f32 v180, -v178, v179, 1.0
	v_fmac_f32_e32 v179, v180, v179
	v_div_scale_f32 v180, vcc, s95, v88, s95
	v_mul_f32_e32 v181, v180, v179
	v_fma_f32 v182, -v178, v181, v180
	v_fmac_f32_e32 v181, v182, v179
	v_fma_f32 v178, -v178, v181, v180
	v_div_fmas_f32 v178, v178, v179, v181
	v_div_fixup_f32 v88, v178, v88, s95
	v_lshlrev_b32_e32 v84, 5, v211
	ds_bpermute_b32 v89, v84, v88
	ds_bpermute_b32 v90, v84, v88 offset:4
	ds_bpermute_b32 v91, v84, v88 offset:8
	ds_bpermute_b32 v92, v84, v88 offset:12
	ds_bpermute_b32 v93, v84, v88 offset:16
	ds_bpermute_b32 v94, v84, v88 offset:20
	ds_bpermute_b32 v95, v84, v88 offset:24
	ds_bpermute_b32 v96, v84, v88 offset:28
	ds_bpermute_b32 v97, v84, v88 offset:32
	ds_bpermute_b32 v98, v84, v88 offset:36
	ds_bpermute_b32 v99, v84, v88 offset:40
	ds_bpermute_b32 v100, v84, v88 offset:44
	ds_bpermute_b32 v101, v84, v88 offset:48
	ds_bpermute_b32 v102, v84, v88 offset:52
	ds_bpermute_b32 v103, v84, v88 offset:56
	ds_bpermute_b32 v104, v84, v88 offset:60
	s_waitcnt vmcnt(0) lgkmcnt(0)
; __device__ __forceinline__ int crow(int r, int hi) { return (r & 3) + 8 * (r >> 2) + 4 * hi; }
; __device__ __forceinline__ void attn_unit(LAS unsigned char* lds, bf16_t* Zg, const unsigned char* KVg, int S, int b, int h, int qb, const float* lq1, const float* lk1, const float* lq2, const float* lk2, const float* subln_g, const float* rel_bias, bool dostore = true) {
;     ...
;         for (int db = 0; db < 4; ++db) { const float sg = subln_g[db * 32 + r32];
; #pragma unroll
;             for (int r = 0; r < 16; ++r) exch[(32 * qsub + crow(r, hi)) * 128 + db * 32 + r32] = o[db][r] * ss[r] * sg; }
	v_mul_f32_e32 v50, v50, v89
	v_mul_f32_e32 v50, v50, v190
	v_mul_f32_e32 v34, v34, v89
	v_mul_f32_e32 v34, v34, v191
	ds_write2_b32 v0, v50, v34 offset1:32
	v_mul_f32_e32 v18, v18, v89
	v_mul_f32_e32 v18, v18, v192
	v_mul_f32_e32 v2, v2, v89
	v_mul_f32_e32 v2, v2, v193
	ds_write2_b32 v0, v18, v2 offset0:64 offset1:96
	v_mul_f32_e32 v51, v51, v90
	v_mul_f32_e32 v51, v51, v190
	v_mul_f32_e32 v35, v35, v90
	v_mul_f32_e32 v35, v35, v191
	ds_write2_b32 v0, v51, v35 offset0:128 offset1:160
	v_mul_f32_e32 v19, v19, v90
	v_mul_f32_e32 v19, v19, v192
	v_mul_f32_e32 v3, v3, v90
	v_mul_f32_e32 v3, v3, v193
	ds_write2_b32 v0, v19, v3 offset0:192 offset1:224
	v_mul_f32_e32 v52, v52, v91
	v_mul_f32_e32 v52, v52, v190
	v_mul_f32_e32 v36, v36, v91
	v_mul_f32_e32 v36, v36, v191
	ds_write2_b32 v105, v52, v36 offset1:32
	v_mul_f32_e32 v20, v20, v91
	v_mul_f32_e32 v20, v20, v192
	v_mul_f32_e32 v4, v4, v91
	v_mul_f32_e32 v4, v4, v193
	ds_write2_b32 v105, v20, v4 offset0:64 offset1:96
	v_mul_f32_e32 v53, v53, v92
	v_mul_f32_e32 v53, v53, v190
	v_mul_f32_e32 v37, v37, v92
	v_mul_f32_e32 v37, v37, v191
	ds_write2_b32 v105, v53, v37 offset0:128 offset1:160
	v_mul_f32_e32 v21, v21, v92
	v_mul_f32_e32 v21, v21, v192
	v_mul_f32_e32 v5, v5, v92
	v_mul_f32_e32 v5, v5, v193
	ds_write2_b32 v105, v21, v5 offset0:192 offset1:224
	v_mul_f32_e32 v54, v54, v93
	v_mul_f32_e32 v54, v54, v190
	v_mul_f32_e32 v38, v38, v93
	v_mul_f32_e32 v38, v38, v191
	ds_write2_b32 v106, v54, v38 offset1:32
	v_mul_f32_e32 v22, v22, v93
	v_mul_f32_e32 v22, v22, v192
	v_mul_f32_e32 v6, v6, v93
	v_mul_f32_e32 v6, v6, v193
	ds_write2_b32 v106, v22, v6 offset0:64 offset1:96
	v_mul_f32_e32 v55, v55, v94
	v_mul_f32_e32 v55, v55, v190
	v_mul_f32_e32 v39, v39, v94
	v_mul_f32_e32 v39, v39, v191
	ds_write2_b32 v106, v55, v39 offset0:128 offset1:160
	v_mul_f32_e32 v23, v23, v94
	v_mul_f32_e32 v23, v23, v192
	v_mul_f32_e32 v7, v7, v94
	v_mul_f32_e32 v7, v7, v193
	ds_write2_b32 v106, v23, v7 offset0:192 offset1:224
	v_mul_f32_e32 v56, v56, v95
	v_mul_f32_e32 v56, v56, v190
	v_mul_f32_e32 v40, v40, v95
	v_mul_f32_e32 v40, v40, v191
	ds_write2_b32 v107, v56, v40 offset1:32
	v_mul_f32_e32 v24, v24, v95
	v_mul_f32_e32 v24, v24, v192
	v_mul_f32_e32 v8, v8, v95
	v_mul_f32_e32 v8, v8, v193
	ds_write2_b32 v107, v24, v8 offset0:64 offset1:96
	v_mul_f32_e32 v57, v57, v96
	v_mul_f32_e32 v57, v57, v190
	v_mul_f32_e32 v41, v41, v96
	v_mul_f32_e32 v41, v41, v191
	ds_write2_b32 v107, v57, v41 offset0:128 offset1:160
	v_mul_f32_e32 v25, v25, v96
	v_mul_f32_e32 v25, v25, v192
	v_mul_f32_e32 v9, v9, v96
	v_mul_f32_e32 v9, v9, v193
	ds_write2_b32 v107, v25, v9 offset0:192 offset1:224
	v_mul_f32_e32 v58, v58, v97
	v_mul_f32_e32 v58, v58, v190
	v_mul_f32_e32 v42, v42, v97
	v_mul_f32_e32 v42, v42, v191
	ds_write2_b32 v108, v58, v42 offset1:32
	v_mul_f32_e32 v26, v26, v97
	v_mul_f32_e32 v26, v26, v192
	v_mul_f32_e32 v10, v10, v97
	v_mul_f32_e32 v10, v10, v193
	ds_write2_b32 v108, v26, v10 offset0:64 offset1:96
	v_mul_f32_e32 v59, v59, v98
	v_mul_f32_e32 v59, v59, v190
	v_mul_f32_e32 v43, v43, v98
	v_mul_f32_e32 v43, v43, v191
	ds_write2_b32 v108, v59, v43 offset0:128 offset1:160
	v_mul_f32_e32 v27, v27, v98
	v_mul_f32_e32 v27, v27, v192
	v_mul_f32_e32 v11, v11, v98
	v_mul_f32_e32 v11, v11, v193
	ds_write2_b32 v108, v27, v11 offset0:192 offset1:224
	v_mul_f32_e32 v60, v60, v99
	v_mul_f32_e32 v60, v60, v190
	v_mul_f32_e32 v44, v44, v99
	v_mul_f32_e32 v44, v44, v191
	ds_write2_b32 v109, v60, v44 offset1:32
	v_mul_f32_e32 v28, v28, v99
	v_mul_f32_e32 v28, v28, v192
	v_mul_f32_e32 v12, v12, v99
	v_mul_f32_e32 v12, v12, v193
	ds_write2_b32 v109, v28, v12 offset0:64 offset1:96
	v_mul_f32_e32 v61, v61, v100
	v_mul_f32_e32 v61, v61, v190
	v_mul_f32_e32 v45, v45, v100
	v_mul_f32_e32 v45, v45, v191
	ds_write2_b32 v109, v61, v45 offset0:128 offset1:160
	v_mul_f32_e32 v29, v29, v100
	v_mul_f32_e32 v29, v29, v192
	v_mul_f32_e32 v13, v13, v100
	v_mul_f32_e32 v13, v13, v193
	ds_write2_b32 v109, v29, v13 offset0:192 offset1:224
	v_mul_f32_e32 v62, v62, v101
	v_mul_f32_e32 v62, v62, v190
	v_mul_f32_e32 v46, v46, v101
	v_mul_f32_e32 v46, v46, v191
	ds_write2_b32 v110, v62, v46 offset1:32
	v_mul_f32_e32 v30, v30, v101
	v_mul_f32_e32 v30, v30, v192
	v_mul_f32_e32 v14, v14, v101
	v_mul_f32_e32 v14, v14, v193
	ds_write2_b32 v110, v30, v14 offset0:64 offset1:96
	v_mul_f32_e32 v63, v63, v102
	v_mul_f32_e32 v63, v63, v190
	v_mul_f32_e32 v47, v47, v102
	v_mul_f32_e32 v47, v47, v191
	ds_write2_b32 v110, v63, v47 offset0:128 offset1:160
	v_mul_f32_e32 v31, v31, v102
	v_mul_f32_e32 v31, v31, v192
	v_mul_f32_e32 v15, v15, v102
	v_mul_f32_e32 v15, v15, v193
	ds_write2_b32 v110, v31, v15 offset0:192 offset1:224
	v_mul_f32_e32 v64, v64, v103
	v_mul_f32_e32 v64, v64, v190
	v_mul_f32_e32 v48, v48, v103
	v_mul_f32_e32 v48, v48, v191
	ds_write2_b32 v111, v64, v48 offset1:32
	v_mul_f32_e32 v32, v32, v103
	v_mul_f32_e32 v32, v32, v192
	v_mul_f32_e32 v16, v16, v103
	v_mul_f32_e32 v16, v16, v193
	ds_write2_b32 v111, v32, v16 offset0:64 offset1:96
	v_mul_f32_e32 v65, v65, v104
	v_mul_f32_e32 v65, v65, v190
	v_mul_f32_e32 v49, v49, v104
	v_mul_f32_e32 v49, v49, v191
	ds_write2_b32 v111, v65, v49 offset0:128 offset1:160
	v_mul_f32_e32 v33, v33, v104
	v_mul_f32_e32 v33, v33, v192
	v_mul_f32_e32 v17, v17, v104
	v_mul_f32_e32 v17, v17, v193
	ds_write2_b32 v111, v33, v17 offset0:192 offset1:224
	s_branch .LBB0_187
